# attention: static s_setprio 1 over the whole P.V+QK MFMA half, row-sum as 4 independent pk_add chains
# baseline (speedup 1.0000x reference)
.Latt_b_exp:
	v_exp_f32_e32 v96, v96
	v_exp_f32_e32 v97, v97
	v_exp_f32_e32 v176, v80
	v_exp_f32_e32 v177, v81
	v_exp_f32_e32 v98, v98
	v_exp_f32_e32 v99, v99
	v_exp_f32_e32 v178, v82
	v_exp_f32_e32 v179, v83
	v_exp_f32_e32 v100, v100
	v_exp_f32_e32 v101, v101
	v_exp_f32_e32 v180, v84
	v_exp_f32_e32 v181, v85
	v_exp_f32_e32 v102, v102
	v_exp_f32_e32 v103, v103
	v_exp_f32_e32 v182, v86
	v_exp_f32_e32 v183, v87
	v_exp_f32_e32 v104, v104
	v_exp_f32_e32 v105, v105
	v_exp_f32_e32 v184, v88
	v_exp_f32_e32 v185, v89
	v_exp_f32_e32 v106, v106
	v_exp_f32_e32 v107, v107
	v_exp_f32_e32 v186, v90
	v_exp_f32_e32 v187, v91
	v_exp_f32_e32 v108, v108
	v_exp_f32_e32 v109, v109
	v_exp_f32_e32 v188, v92
	v_exp_f32_e32 v189, v93
	v_exp_f32_e32 v110, v110
	v_exp_f32_e32 v111, v111
	v_exp_f32_e32 v190, v94
	v_exp_f32_e32 v191, v95
	v_cvt_pk_bf16_f32 v80, v96, v97
	v_cvt_pk_bf16_f32 v81, v98, v99
	v_cvt_pk_bf16_f32 v82, v100, v101
	v_cvt_pk_bf16_f32 v83, v102, v103
	v_cvt_pk_bf16_f32 v84, v104, v105
	v_cvt_pk_bf16_f32 v85, v106, v107
	v_cvt_pk_bf16_f32 v86, v108, v109
	v_cvt_pk_bf16_f32 v87, v110, v111
	v_cvt_pk_bf16_f32 v88, v176, v177
	v_cvt_pk_bf16_f32 v89, v178, v179
	v_cvt_pk_bf16_f32 v90, v180, v181
	v_cvt_pk_bf16_f32 v91, v182, v183
	v_cvt_pk_bf16_f32 v92, v184, v185
	v_cvt_pk_bf16_f32 v93, v186, v187
	v_cvt_pk_bf16_f32 v94, v188, v189
	v_cvt_pk_bf16_f32 v95, v190, v191
	v_pk_add_f32 v[96:97], v[96:97], v[100:101]
	v_pk_add_f32 v[98:99], v[98:99], v[102:103]
	v_pk_add_f32 v[176:177], v[176:177], v[180:181]
	v_pk_add_f32 v[178:179], v[178:179], v[182:183]
	v_pk_add_f32 v[96:97], v[96:97], v[104:105]
	v_pk_add_f32 v[98:99], v[98:99], v[106:107]
	v_pk_add_f32 v[176:177], v[176:177], v[184:185]
	v_pk_add_f32 v[178:179], v[178:179], v[186:187]
	v_pk_add_f32 v[96:97], v[96:97], v[108:109]
	v_pk_add_f32 v[98:99], v[98:99], v[110:111]
	v_pk_add_f32 v[176:177], v[176:177], v[188:189]
	v_pk_add_f32 v[178:179], v[178:179], v[190:191]
	v_pk_add_f32 v[96:97], v[96:97], v[98:99]
	v_pk_add_f32 v[176:177], v[176:177], v[178:179]
	s_nop 0
	v_pk_add_f32 v[96:97], v[96:97], v[176:177]
	s_nop 0
	v_add_f32_e32 v96, v96, v97
	v_add_f32_e32 v172, v172, v96
.Latt_b_bar:
	s_waitcnt lgkmcnt(0)
	s_barrier
	s_cmp_gt_i32 s86, s9
	s_cbranch_scc1 .LBB0_241
	s_cmp_ge_i32 s86, s9
	s_cbranch_scc1 .Latt_b_pvonly
	s_mul_i32 s4, s69, 0x5000
	v_add_u32_e32 v205, s4, v165
	v_add_u32_e32 v206, s28, v192
	ds_read_b64_tr_b16 v[96:97], v205 offset:34816
	ds_read_b64_tr_b16 v[98:99], v205 offset:37376
	ds_read_b64_tr_b16 v[100:101], v205 offset:39936
	ds_read_b64_tr_b16 v[102:103], v205 offset:42496
	ds_read_b64_tr_b16 v[104:105], v205 offset:45056
	ds_read_b64_tr_b16 v[106:107], v205 offset:47616
	ds_read_b64_tr_b16 v[108:109], v205 offset:50176
	ds_read_b64_tr_b16 v[110:111], v205 offset:52736
	ds_read_b64_tr_b16 v[176:177], v205 offset:34880
	ds_read_b64_tr_b16 v[178:179], v205 offset:37440
	ds_read_b64_tr_b16 v[180:181], v205 offset:40000
	ds_read_b64_tr_b16 v[182:183], v205 offset:42560
	ds_read_b64_tr_b16 v[184:185], v205 offset:45120
	ds_read_b64_tr_b16 v[186:187], v205 offset:47680
	s_setprio 1
	s_waitcnt lgkmcnt(12)
	v_mfma_f32_32x32x16_bf16 v[32:47], v[96:99], v[80:83], v[32:47]
	ds_read_b64_tr_b16 v[96:97], v205 offset:50240
	ds_read_b64_tr_b16 v[98:99], v205 offset:52800
	s_waitcnt lgkmcnt(12)
	v_mfma_f32_32x32x16_bf16 v[32:47], v[100:103], v[84:87], v[32:47]
	ds_read_b64_tr_b16 v[100:101], v205 offset:34944
	ds_read_b64_tr_b16 v[102:103], v205 offset:37504
	s_waitcnt lgkmcnt(12)
	v_mfma_f32_32x32x16_bf16 v[32:47], v[104:107], v[88:91], v[32:47]
	ds_read_b64_tr_b16 v[104:105], v205 offset:40064
	ds_read_b64_tr_b16 v[106:107], v205 offset:42624
	s_waitcnt lgkmcnt(12)
	v_mfma_f32_32x32x16_bf16 v[32:47], v[108:111], v[92:95], v[32:47]
	ds_read_b64_tr_b16 v[108:109], v205 offset:45184
	ds_read_b64_tr_b16 v[110:111], v205 offset:47744
	s_waitcnt lgkmcnt(12)
	v_mfma_f32_32x32x16_bf16 v[16:31], v[176:179], v[80:83], v[16:31]
	ds_read_b64_tr_b16 v[176:177], v205 offset:50304
	ds_read_b64_tr_b16 v[178:179], v205 offset:52864
	s_waitcnt lgkmcnt(12)
	v_mfma_f32_32x32x16_bf16 v[16:31], v[180:183], v[84:87], v[16:31]
	ds_read_b64_tr_b16 v[180:181], v205 offset:35008
	ds_read_b64_tr_b16 v[182:183], v205 offset:37568
	s_waitcnt lgkmcnt(12)
	v_mfma_f32_32x32x16_bf16 v[16:31], v[184:187], v[88:91], v[16:31]
	ds_read_b64_tr_b16 v[184:185], v205 offset:40128
	ds_read_b64_tr_b16 v[186:187], v205 offset:42688
	s_waitcnt lgkmcnt(12)
	v_mfma_f32_32x32x16_bf16 v[16:31], v[96:99], v[92:95], v[16:31]
	ds_read_b64_tr_b16 v[96:97], v205 offset:45248
	ds_read_b64_tr_b16 v[98:99], v205 offset:47808
	s_waitcnt lgkmcnt(12)
	v_mfma_f32_32x32x16_bf16 v[0:15], v[100:103], v[80:83], v[0:15]
	ds_read_b64_tr_b16 v[100:101], v205 offset:50368
	ds_read_b64_tr_b16 v[102:103], v205 offset:52928
	s_waitcnt lgkmcnt(12)
	v_mfma_f32_32x32x16_bf16 v[0:15], v[104:107], v[84:87], v[0:15]
	ds_read_b128 v[210:213], v206 offset:8704
	ds_read_b128 v[104:107], v206 offset:8736
	s_waitcnt lgkmcnt(12)
	v_mfma_f32_32x32x16_bf16 v[0:15], v[108:111], v[88:91], v[0:15]
	ds_read_b128 v[108:111], v206 offset:8768
	ds_read_b128 v[188:191], v206
	s_waitcnt lgkmcnt(12)
	v_mfma_f32_32x32x16_bf16 v[0:15], v[176:179], v[92:95], v[0:15]
	ds_read_b128 v[176:179], v206 offset:8800
	ds_read_b128 v[224:227], v206 offset:32
	s_waitcnt lgkmcnt(12)
	v_mfma_f32_32x32x16_bf16 v[48:63], v[180:183], v[80:83], v[48:63]
	ds_read_b128 v[228:231], v206 offset:64
	ds_read_b128 v[248:251], v206 offset:96
	s_waitcnt lgkmcnt(12)
	v_mfma_f32_32x32x16_bf16 v[48:63], v[184:187], v[84:87], v[48:63]
	s_waitcnt lgkmcnt(10)
	v_mfma_f32_32x32x16_bf16 v[48:63], v[96:99], v[88:91], v[48:63]
	s_waitcnt lgkmcnt(8)
	v_mfma_f32_32x32x16_bf16 v[48:63], v[100:103], v[92:95], v[48:63]
	s_waitcnt lgkmcnt(7)
	v_mfma_f32_32x32x16_bf16 v[80:95], v[210:213], v[112:115], v[64:79]
	s_waitcnt lgkmcnt(6)
	v_mfma_f32_32x32x16_bf16 v[80:95], v[104:107], v[116:119], v[80:95]
	s_waitcnt lgkmcnt(5)
	v_mfma_f32_32x32x16_bf16 v[80:95], v[108:111], v[120:123], v[80:95]
	s_waitcnt lgkmcnt(3)
	v_mfma_f32_32x32x16_bf16 v[80:95], v[176:179], v[124:127], v[80:95]
	s_waitcnt lgkmcnt(4)
	v_mfma_f32_32x32x16_bf16 v[96:111], v[188:191], v[112:115], v[64:79]
	s_waitcnt lgkmcnt(2)
	v_mfma_f32_32x32x16_bf16 v[96:111], v[224:227], v[116:119], v[96:111]
	s_waitcnt lgkmcnt(1)
	v_mfma_f32_32x32x16_bf16 v[96:111], v[228:231], v[120:123], v[96:111]
	s_waitcnt lgkmcnt(0)
	v_mfma_f32_32x32x16_bf16 v[96:111], v[248:251], v[124:127], v[96:111]
	s_setprio 0
	s_cmp_gt_i32 s33, 3
	s_cbranch_scc1 .LBB0_241
	s_waitcnt lgkmcnt(0)
	s_add_i32 s4, s68, 0x100
	v_add_u32_e32 v205, s4, v204
	v_add_u32_e32 v176, 0x17d00, v205
	v_add_u32_e32 v178, 0x17d80, v205
	ds_read2_b32 v[176:177], v176 offset1:1
	ds_read2_b32 v[178:179], v178 offset1:1
	v_add_u32_e32 v180, 0x17d08, v205
	v_add_u32_e32 v182, 0x17d88, v205
	v_add_u32_e32 v184, 0x17d20, v205
	v_add_u32_e32 v186, 0x17da0, v205
	v_add_u32_e32 v188, 0x17d28, v205
	v_add_u32_e32 v190, 0x17da8, v205
	v_add_u32_e32 v206, 0x17d40, v205
	v_add_u32_e32 v210, 0x17dc0, v205
	v_add_u32_e32 v212, 0x17d48, v205
	v_add_u32_e32 v221, 0x17dc8, v205
	ds_read2_b32 v[180:181], v180 offset1:1
	ds_read2_b32 v[182:183], v182 offset1:1
	ds_read2_b32 v[184:185], v184 offset1:1
	ds_read2_b32 v[186:187], v186 offset1:1
	ds_read2_b32 v[188:189], v188 offset1:1
	ds_read2_b32 v[190:191], v190 offset1:1
	ds_read2_b32 v[206:207], v206 offset1:1
	ds_read2_b32 v[210:211], v210 offset1:1
	ds_read2_b32 v[212:213], v212 offset1:1
	ds_read2_b32 v[224:225], v221 offset1:1
	v_add_u32_e32 v221, 0x17d60, v205
	v_add_u32_e32 v223, 0x17de0, v205
	ds_read2_b32 v[226:227], v221 offset1:1
	ds_read2_b32 v[228:229], v223 offset1:1
	v_add_u32_e32 v221, 0x17d68, v205
	v_add_u32_e32 v205, 0x17de8, v205
	ds_read2_b32 v[230:231], v221 offset1:1
	s_waitcnt lgkmcnt(14)
	v_pk_add_f32 v[96:97], v[96:97], v[176:177]
	ds_read2_b32 v[176:177], v205 offset1:1
	s_waitcnt lgkmcnt(3)
	v_pk_add_f32 v[108:109], v[108:109], v[226:227]
	v_pk_add_f32 v[106:107], v[106:107], v[212:213]
	s_waitcnt lgkmcnt(1)
	v_pk_add_f32 v[110:111], v[110:111], v[230:231]
	v_pk_add_f32 v[104:105], v[104:105], v[206:207]
	v_pk_add_f32 v[102:103], v[102:103], v[188:189]
	v_pk_add_f32 v[100:101], v[100:101], v[184:185]
	v_pk_add_f32 v[98:99], v[98:99], v[180:181]
	s_waitcnt lgkmcnt(0)
	v_pk_add_f32 v[94:95], v[94:95], v[176:177]
	v_pk_add_f32 v[92:93], v[92:93], v[228:229]
	v_pk_add_f32 v[90:91], v[90:91], v[224:225]
	v_pk_add_f32 v[88:89], v[88:89], v[210:211]
	v_pk_add_f32 v[86:87], v[86:87], v[190:191]
	v_pk_add_f32 v[84:85], v[84:85], v[186:187]
	v_pk_add_f32 v[82:83], v[82:83], v[182:183]
	v_pk_add_f32 v[80:81], v[80:81], v[178:179]
	s_nop 0
	s_branch .LBB0_241

.Latt_a:
	s_mul_i32 s4, s87, 0x5000
	v_add_u32_e32 v205, s4, v165
	v_add_u32_e32 v206, s5, v192
	ds_read_b64_tr_b16 v[96:97], v205 offset:34816
	ds_read_b64_tr_b16 v[98:99], v205 offset:37376
	ds_read_b64_tr_b16 v[100:101], v205 offset:39936
	ds_read_b64_tr_b16 v[102:103], v205 offset:42496
	ds_read_b64_tr_b16 v[104:105], v205 offset:45056
	ds_read_b64_tr_b16 v[106:107], v205 offset:47616
	ds_read_b64_tr_b16 v[108:109], v205 offset:50176
	ds_read_b64_tr_b16 v[110:111], v205 offset:52736
	ds_read_b64_tr_b16 v[176:177], v205 offset:34880
	ds_read_b64_tr_b16 v[178:179], v205 offset:37440
	ds_read_b64_tr_b16 v[180:181], v205 offset:40000
	ds_read_b64_tr_b16 v[182:183], v205 offset:42560
	ds_read_b64_tr_b16 v[184:185], v205 offset:45120
	ds_read_b64_tr_b16 v[186:187], v205 offset:47680
	s_setprio 1
	s_waitcnt lgkmcnt(12)
	v_mfma_f32_32x32x16_bf16 v[32:47], v[96:99], v[80:83], v[32:47]
	ds_read_b64_tr_b16 v[96:97], v205 offset:50240
	ds_read_b64_tr_b16 v[98:99], v205 offset:52800
	s_waitcnt lgkmcnt(12)
	v_mfma_f32_32x32x16_bf16 v[32:47], v[100:103], v[84:87], v[32:47]
	ds_read_b64_tr_b16 v[100:101], v205 offset:34944
	ds_read_b64_tr_b16 v[102:103], v205 offset:37504
	s_waitcnt lgkmcnt(12)
	v_mfma_f32_32x32x16_bf16 v[32:47], v[104:107], v[88:91], v[32:47]
	ds_read_b64_tr_b16 v[104:105], v205 offset:40064
	ds_read_b64_tr_b16 v[106:107], v205 offset:42624
	s_waitcnt lgkmcnt(12)
	v_mfma_f32_32x32x16_bf16 v[32:47], v[108:111], v[92:95], v[32:47]
	ds_read_b64_tr_b16 v[108:109], v205 offset:45184
	ds_read_b64_tr_b16 v[110:111], v205 offset:47744
	s_waitcnt lgkmcnt(12)
	v_mfma_f32_32x32x16_bf16 v[16:31], v[176:179], v[80:83], v[16:31]
	ds_read_b64_tr_b16 v[176:177], v205 offset:50304
	ds_read_b64_tr_b16 v[178:179], v205 offset:52864
	s_waitcnt lgkmcnt(12)
	v_mfma_f32_32x32x16_bf16 v[16:31], v[180:183], v[84:87], v[16:31]
	ds_read_b64_tr_b16 v[180:181], v205 offset:35008
	ds_read_b64_tr_b16 v[182:183], v205 offset:37568
	s_waitcnt lgkmcnt(12)
	v_mfma_f32_32x32x16_bf16 v[16:31], v[184:187], v[88:91], v[16:31]
	ds_read_b64_tr_b16 v[184:185], v205 offset:40128
	ds_read_b64_tr_b16 v[186:187], v205 offset:42688
	s_waitcnt lgkmcnt(12)
	v_mfma_f32_32x32x16_bf16 v[16:31], v[96:99], v[92:95], v[16:31]
	ds_read_b64_tr_b16 v[96:97], v205 offset:45248
	ds_read_b64_tr_b16 v[98:99], v205 offset:47808
	s_waitcnt lgkmcnt(12)
	v_mfma_f32_32x32x16_bf16 v[0:15], v[100:103], v[80:83], v[0:15]
	ds_read_b64_tr_b16 v[100:101], v205 offset:50368
	ds_read_b64_tr_b16 v[102:103], v205 offset:52928
	s_waitcnt lgkmcnt(12)
	v_mfma_f32_32x32x16_bf16 v[0:15], v[104:107], v[84:87], v[0:15]
	ds_read_b128 v[210:213], v206 offset:8704
	ds_read_b128 v[104:107], v206 offset:8736
	s_waitcnt lgkmcnt(12)
	v_mfma_f32_32x32x16_bf16 v[0:15], v[108:111], v[88:91], v[0:15]
	ds_read_b128 v[108:111], v206 offset:8768
	ds_read_b128 v[188:191], v206
	s_waitcnt lgkmcnt(12)
	v_mfma_f32_32x32x16_bf16 v[0:15], v[176:179], v[92:95], v[0:15]
	ds_read_b128 v[176:179], v206 offset:8800
	ds_read_b128 v[224:227], v206 offset:32
	s_waitcnt lgkmcnt(12)
	v_mfma_f32_32x32x16_bf16 v[48:63], v[180:183], v[80:83], v[48:63]
	ds_read_b128 v[228:231], v206 offset:64
	ds_read_b128 v[248:251], v206 offset:96
	s_waitcnt lgkmcnt(12)
	v_mfma_f32_32x32x16_bf16 v[48:63], v[184:187], v[84:87], v[48:63]
	s_waitcnt lgkmcnt(10)
	v_mfma_f32_32x32x16_bf16 v[48:63], v[96:99], v[88:91], v[48:63]
	s_waitcnt lgkmcnt(8)
	v_mfma_f32_32x32x16_bf16 v[48:63], v[100:103], v[92:95], v[48:63]
	s_waitcnt lgkmcnt(7)
	v_mfma_f32_32x32x16_bf16 v[80:95], v[210:213], v[112:115], v[64:79]
	s_waitcnt lgkmcnt(6)
	v_mfma_f32_32x32x16_bf16 v[80:95], v[104:107], v[116:119], v[80:95]
	s_waitcnt lgkmcnt(5)
	v_mfma_f32_32x32x16_bf16 v[80:95], v[108:111], v[120:123], v[80:95]
	s_waitcnt lgkmcnt(3)
	v_mfma_f32_32x32x16_bf16 v[80:95], v[176:179], v[124:127], v[80:95]
	s_waitcnt lgkmcnt(4)
	v_mfma_f32_32x32x16_bf16 v[96:111], v[188:191], v[112:115], v[64:79]
	s_waitcnt lgkmcnt(2)
	v_mfma_f32_32x32x16_bf16 v[96:111], v[224:227], v[116:119], v[96:111]
	s_waitcnt lgkmcnt(1)
	v_mfma_f32_32x32x16_bf16 v[96:111], v[228:231], v[120:123], v[96:111]
	s_waitcnt lgkmcnt(0)
	v_mfma_f32_32x32x16_bf16 v[96:111], v[248:251], v[124:127], v[96:111]
	s_setprio 0
	s_cmp_gt_i32 s33, 2
	s_cbranch_scc1 .Latt_a_stg
	s_waitcnt lgkmcnt(0)
	v_add_u32_e32 v205, s68, v204
	v_add_u32_e32 v176, 0x17d00, v205
	v_add_u32_e32 v178, 0x17d80, v205
	ds_read2_b32 v[176:177], v176 offset1:1
	ds_read2_b32 v[178:179], v178 offset1:1
	v_add_u32_e32 v180, 0x17d08, v205
	v_add_u32_e32 v182, 0x17d88, v205
	v_add_u32_e32 v184, 0x17d20, v205
	v_add_u32_e32 v186, 0x17da0, v205
	v_add_u32_e32 v188, 0x17d28, v205
	v_add_u32_e32 v190, 0x17da8, v205
	v_add_u32_e32 v206, 0x17d40, v205
	v_add_u32_e32 v210, 0x17dc0, v205
	v_add_u32_e32 v212, 0x17d48, v205
	v_add_u32_e32 v221, 0x17dc8, v205
	ds_read2_b32 v[180:181], v180 offset1:1
	ds_read2_b32 v[182:183], v182 offset1:1
	ds_read2_b32 v[184:185], v184 offset1:1
	ds_read2_b32 v[186:187], v186 offset1:1
	ds_read2_b32 v[188:189], v188 offset1:1
	ds_read2_b32 v[190:191], v190 offset1:1
	ds_read2_b32 v[206:207], v206 offset1:1
	ds_read2_b32 v[210:211], v210 offset1:1
	ds_read2_b32 v[212:213], v212 offset1:1
	ds_read2_b32 v[224:225], v221 offset1:1
	v_add_u32_e32 v221, 0x17d60, v205
	v_add_u32_e32 v223, 0x17de0, v205
	ds_read2_b32 v[226:227], v221 offset1:1
	ds_read2_b32 v[228:229], v223 offset1:1
	v_add_u32_e32 v221, 0x17d68, v205
	v_add_u32_e32 v205, 0x17de8, v205
	ds_read2_b32 v[230:231], v221 offset1:1
	s_waitcnt lgkmcnt(14)
	v_pk_add_f32 v[96:97], v[96:97], v[176:177]
	ds_read2_b32 v[176:177], v205 offset1:1
	s_waitcnt lgkmcnt(3)
	v_pk_add_f32 v[108:109], v[108:109], v[226:227]
	v_pk_add_f32 v[106:107], v[106:107], v[212:213]
	s_waitcnt lgkmcnt(1)
	v_pk_add_f32 v[110:111], v[110:111], v[230:231]
	v_pk_add_f32 v[104:105], v[104:105], v[206:207]
	v_pk_add_f32 v[102:103], v[102:103], v[188:189]
	v_pk_add_f32 v[100:101], v[100:101], v[184:185]
	v_pk_add_f32 v[98:99], v[98:99], v[180:181]
	s_waitcnt lgkmcnt(0)
	v_pk_add_f32 v[94:95], v[94:95], v[176:177]
	v_pk_add_f32 v[92:93], v[92:93], v[228:229]
	v_pk_add_f32 v[90:91], v[90:91], v[224:225]
	v_pk_add_f32 v[88:89], v[88:89], v[210:211]
	v_pk_add_f32 v[86:87], v[86:87], v[190:191]
	v_pk_add_f32 v[84:85], v[84:85], v[186:187]
	v_pk_add_f32 v[82:83], v[82:83], v[182:183]
	v_pk_add_f32 v[80:81], v[80:81], v[178:179]
	s_nop 0
